# attention: prefetch first K fragments across the tile barrier + pipeline body-B K reads one step ahead
# baseline (speedup 1.0000x reference)
; #define LAS __attribute__((address_space(3)))
; __device__ __forceinline__ int v_st(int k, int c) { const int kk = k; return ((kk >> 3) * 4 + (c >> 5)) * 512 + ((kk & 7) * 32 + (c & 31)) * 2; }
; __device__ __forceinline__ int v_rd_base(int lane) { return ((lane & 3) << 3) | (((lane >> 2) & 3) << 6) | (((lane >> 4) & 1) << 5) | (((lane >> 5) & 1) << 8); }
; #define ABAR() asm volatile("s_waitcnt lgkmcnt(0)\n\ts_barrier" ::: "memory")
; #define SLOAD(i, k0) do { const bf16_t* vt_ = Vh + (size_t)(k0) * 512; const bf16_t* kt_ = KNh + (size_t)(k0) * 512; const bf16_t* rt_ = KRb + (size_t)(k0) * 32; \
;     sr_[i].vs = *reinterpret_cast<const bf16x8*>(vt_ + lo_kv); sr_[i].ks = *reinterpret_cast<const bf16x8*>(kt_ + lo_kv); sr_[i].kr = *reinterpret_cast<const s16x4*>(rt_ + lo_kr); } while (0)
; #define SWRITE(slot, i) do { *(bf16x8*)(V_lds + (slot) * SHM_V + vst) = sr_[i].vs; *(bf16x8*)(K_lds + (slot) * SHM_K + kst) = sr_[i].ks; *(s16x4*)(K_lds + (slot) * SHM_K + krst) = sr_[i].kr; } while (0)
; __device__ __forceinline__ void attn_unit(const bf16_t* __restrict__ Qb, const bf16_t* __restrict__ KNh, const bf16_t* __restrict__ KRb, const bf16_t* __restrict__ Vh, bf16_t* __restrict__ Ob, char* lds) {
;     ...
;   float mref = 0.f, l_reg = 0; f32x16 negm = {}; f32x16 o[2] = {}; bf16x8 qr[6];
;   const bf16_t* Qw = Qb + (long)(wid * QBLK + r32) * 768 + hi * 8;
; #pragma unroll
;   for (int d0 = 0; d0 < 6; ++d0) qr[d0] = *reinterpret_cast<const bf16x8*>(Qw + d0 * 16);
;   const int sr = tid >> 3, sc = (tid & 7) * 8, vst = v_st(sr, sc), kst = KSWZ(sr, sc * 2), krst = KSWZ(sr, 128 + (tid & 7) * 8);
;   const lds_cptr vb0 = (lds_cptr)(LAS char*)lds + v_rd_base(lane);
;   struct { bf16x8 vs, ks; s16x4 kr; } sr_[2];
;   const unsigned lo_kv = (unsigned)(sr * 512 + sc), lo_kr = (unsigned)(sr * 32 + (tid & 7) * 4);
;     ...
;   if (__builtin_amdgcn_readfirstlane(tid >> 6) >= 4) __builtin_amdgcn_s_setprio(1);
;   f32x16 pA0, pA1, pB0, pB1; float alA, alB; bf16x8 pa0, pa1, pa2, pa3; constexpr int NT = SEQ / KVBLK;
;   SLOAD(0, 0); SLOAD(1, KVBLK); asm volatile("s_waitcnt vmcnt(0)" ::: "memory"); SWRITE(0, 0); SWRITE(1, 1); SLOAD(0, 2 * KVBLK); ABAR();
;   qkt(pA0, pA1, K_lds, qr, negm, r32, hi); partialSM<true>(pA0, pA1, mref, negm, alA);
;   SWRITE(2, 0); SLOAD(1, 3 * KVBLK); ABAR();
.LBB0_738:
	s_xor_b64 s[34:35], s[30:31], -1
	s_lshr_b32 s91, s33, 3
	s_lshl_b64 s[62:63], s[42:43], 21
	s_add_u32 s44, s14, s62
	s_addc_u32 s45, s15, s63
	s_lshl_b32 s88, s41, 6
	s_lshl_b32 s41, s41, 7
	s_add_u32 s44, s44, s41
	s_addc_u32 s45, s45, 0
	s_lshl_b64 s[64:65], s[42:43], 17
	s_add_u32 s42, s24, s64
	v_readlane_b32 s43, v252, 36
	s_addc_u32 s43, s43, s65
	s_add_u32 s46, s25, s62
	s_addc_u32 s47, s97, s63
	s_add_u32 s46, s46, s41
	s_addc_u32 s47, s47, 0
	v_mov_b32_e32 v169, v153
	v_lshl_add_u64 v[52:53], s[46:47], 0, v[168:169]
	s_mov_b32 s89, 0x10000
	v_add_co_u32_e32 v8, vcc, s89, v52
	v_lshl_add_u64 v[50:51], s[44:45], 0, v[168:169]
	s_nop 0
	v_addc_co_u32_e32 v9, vcc, 0, v53, vcc
	v_add_co_u32_e32 v12, vcc, s89, v50
	global_load_dwordx4 v[0:3], v168, s[46:47]
	s_nop 0
	v_addc_co_u32_e32 v13, vcc, 0, v51, vcc
	global_load_dwordx4 v[4:7], v168, s[44:45]
	global_load_dwordx2 v[16:17], v170, s[42:43]
	s_nop 0
	global_load_dwordx4 v[8:11], v[8:9], off
	s_nop 0
	global_load_dwordx4 v[12:15], v[12:13], off
	v_mov_b32_e32 v171, v153
	v_lshl_add_u64 v[48:49], s[42:43], 0, v[170:171]
	v_add_co_u32_e32 v18, vcc, s70, v48
	v_add_u32_e32 v26, s85, v201
	s_nop 0
	v_addc_co_u32_e32 v19, vcc, 0, v49, vcc
	global_load_dwordx2 v[20:21], v[18:19], off offset:-4096
	v_add_co_u32_e32 v22, vcc, s67, v50
	s_waitcnt vmcnt(0)
	v_add_u32_e32 v27, s85, v202
	s_nop 0
	v_addc_co_u32_e32 v23, vcc, 0, v51, vcc
	v_add_co_u32_e32 v24, vcc, s67, v52
	v_add_u32_e32 v28, s82, v201
	s_nop 0
	v_addc_co_u32_e32 v25, vcc, 0, v53, vcc
	v_add_u32_e32 v29, s82, v202
	global_load_dwordx4 v[136:139], v[24:25], off
	global_load_dwordx4 v[140:143], v[22:23], off
	global_load_dwordx2 v[172:173], v[18:19], off
	v_add_u32_e32 v30, s85, v206
	v_add_co_u32_e32 v62, vcc, s84, v52
	v_add_u32_e32 v64, s85, v211
	s_nop 0
	v_addc_co_u32_e32 v63, vcc, 0, v53, vcc
	s_mov_b32 s41, s40
	s_mov_b32 s42, s40
	s_mov_b32 s43, s40
	s_mov_b32 s44, s40
	s_mov_b32 s45, s40
	s_mov_b32 s46, s40
	s_mov_b32 s47, s40
	s_mov_b32 s48, s40
	s_mov_b32 s49, s40
	s_mov_b32 s50, s40
	s_mov_b32 s51, s40
	s_mov_b32 s52, s40
	s_mov_b32 s53, s40
	s_mov_b32 s54, s40
	s_mov_b32 s55, s40
	s_mov_b32 s90, 1
	v_mov_b32_e32 v177, s65
	v_or_b32_e32 v176, s64, v154
	v_mov_b32_e32 v152, 0
	v_mov_b32_e32 v163, 1.0
	s_waitcnt vmcnt(7)
	ds_write_b128 v26, v[4:7]
	s_waitcnt vmcnt(6)
	ds_write_b64 v27, v[16:17]
	ds_write_b128 v204, v[0:3]
	s_waitcnt vmcnt(5)
	ds_write_b128 v204, v[8:11] offset:16384
	s_waitcnt vmcnt(4)
	ds_write_b128 v28, v[12:15]
	s_waitcnt vmcnt(3)
	ds_write_b64 v29, v[20:21]
	s_waitcnt lgkmcnt(0)
	s_barrier
	ds_read_b128 v[0:3], v30
	ds_read_b128 v[4:7], v30 offset:8192
	s_waitcnt lgkmcnt(1)
	v_mfma_f32_32x32x16_bf16 v[32:47], v[0:3], v[132:135], 0
	v_add_u32_e32 v8, s85, v207
	s_waitcnt lgkmcnt(0)
	v_mfma_f32_32x32x16_bf16 v[16:31], v[4:7], v[132:135], 0
	ds_read_b128 v[0:3], v8
	ds_read_b128 v[4:7], v8 offset:8192
	v_add_u32_e32 v8, s85, v208
	s_waitcnt lgkmcnt(1)
	v_mfma_f32_32x32x16_bf16 v[32:47], v[0:3], v[128:131], v[32:47]
	s_waitcnt lgkmcnt(0)
	v_mfma_f32_32x32x16_bf16 v[16:31], v[4:7], v[128:131], v[16:31]
	ds_read_b128 v[0:3], v8
	ds_read_b128 v[4:7], v8 offset:8192
	v_add_u32_e32 v8, s85, v209
	ds_read_b128 v[58:61], v64
	s_waitcnt lgkmcnt(2)
	v_mfma_f32_32x32x16_bf16 v[32:47], v[0:3], v[124:127], v[32:47]
	ds_read_b128 v[0:3], v8
	s_waitcnt lgkmcnt(2)
	v_mfma_f32_32x32x16_bf16 v[16:31], v[4:7], v[124:127], v[16:31]
	ds_read_b128 v[4:7], v8 offset:8192
	v_add_u32_e32 v8, s85, v210
	ds_read_b128 v[54:57], v8 offset:8192
	s_waitcnt lgkmcnt(2)
	v_mfma_f32_32x32x16_bf16 v[32:47], v[0:3], v[120:123], v[32:47]
	ds_read_b128 v[0:3], v8
	s_waitcnt lgkmcnt(2)
	v_mfma_f32_32x32x16_bf16 v[16:31], v[4:7], v[120:123], v[16:31]
	s_waitcnt lgkmcnt(1)
	v_mfma_f32_32x32x16_bf16 v[16:31], v[54:57], v[116:119], v[16:31]
	v_add_co_u32_e32 v54, vcc, s84, v50
	s_nop 1
	v_addc_co_u32_e32 v55, vcc, 0, v51, vcc
	v_add_co_u32_e32 v48, vcc, s80, v48
	ds_read_b128 v[50:53], v64 offset:8192
	s_nop 0
	v_addc_co_u32_e32 v49, vcc, 0, v49, vcc
	global_load_dwordx4 v[144:147], v[62:63], off
	global_load_dwordx4 v[148:151], v[54:55], off
	global_load_dwordx2 v[174:175], v[48:49], off
	s_waitcnt lgkmcnt(1)
	v_mfma_f32_32x32x16_bf16 v[32:47], v[0:3], v[116:119], v[32:47]
	v_mov_b64_e32 v[0:1], s[40:41]
	v_mov_b64_e32 v[2:3], s[42:43]
	v_mov_b64_e32 v[4:5], s[44:45]
	v_mov_b64_e32 v[6:7], s[46:47]
	v_mov_b64_e32 v[8:9], s[48:49]
	v_mov_b64_e32 v[10:11], s[50:51]
	v_mov_b64_e32 v[12:13], s[52:53]
	v_mfma_f32_32x32x16_bf16 v[32:47], v[58:61], v[112:115], v[32:47]
	v_mov_b64_e32 v[14:15], s[54:55]
	s_and_b32 s41, s91, 7
	s_waitcnt vmcnt(5)
	ds_write_b128 v204, v[136:139] offset:32768
	s_lshl_b32 s41, s41, 7
	s_or_b32 s62, s62, s41
	v_lshl_add_u64 v[178:179], s[62:63], 0, v[158:159]
	s_add_u32 s98, s22, s62
	s_addc_u32 s99, s23, s63
	s_add_u32 s98, s98, 0x40000
	s_addc_u32 s99, s99, 0
	s_add_u32 s100, s22, s64
	s_addc_u32 s101, s23, s65
	s_add_u32 s100, s100, 0x4000
	s_addc_u32 s101, s101, 0
	v_add_u32_e32 v240, 0x2a800000, v158
	v_add_u32_e32 v241, 0x26800000, v158
	v_add_u32_e32 v242, 0x2e800000, v154
	s_nop 4
	v_max_f32_e32 v48, v33, v33
	v_max_f32_e32 v49, v32, v32
	s_waitcnt lgkmcnt(1)
; #define ABAR() asm volatile("s_waitcnt lgkmcnt(0)\n\ts_barrier" ::: "memory")
; #define SLOAD(i, k0) do { const bf16_t* vt_ = Vh + (size_t)(k0) * 512; const bf16_t* kt_ = KNh + (size_t)(k0) * 512; const bf16_t* rt_ = KRb + (size_t)(k0) * 32; \
;     sr_[i].vs = *reinterpret_cast<const bf16x8*>(vt_ + lo_kv); sr_[i].ks = *reinterpret_cast<const bf16x8*>(kt_ + lo_kv); sr_[i].kr = *reinterpret_cast<const s16x4*>(rt_ + lo_kr); } while (0)
; #define SWRITE(slot, i) do { *(bf16x8*)(V_lds + (slot) * SHM_V + vst) = sr_[i].vs; *(bf16x8*)(K_lds + (slot) * SHM_K + kst) = sr_[i].ks; *(s16x4*)(K_lds + (slot) * SHM_K + krst) = sr_[i].kr; } while (0)
; template <bool FIRST> __device__ __forceinline__ void partialSM(f32x16& p0, f32x16& p1, float& mref, f32x16& negm, float& alpha) {
;   constexpr float THRL = THR * 1.4426950408889634f;
;   float pmax = p0[0];
; #pragma unroll
;   for (int r = 1; r < 16; ++r) pmax = fmaxf(pmax, p0[r]);
; #pragma unroll
;   for (int r = 0; r < 16; ++r) pmax = fmaxf(pmax, p1[r]);
;   { auto rr = __builtin_amdgcn_permlane32_swap(__float_as_uint(pmax), __float_as_uint(pmax), false, false);
;     pmax = fmaxf(__uint_as_float(rr[0]), __uint_as_float(rr[1])); }
;   if (!FIRST && __builtin_expect(__all(pmax <= THRL), 1)) { alpha = 1.f; }
;   else { const float dl = FIRST ? pmax : fmaxf(pmax, 0.f); mref += dl; alpha = FIRST ? 1.f : __builtin_amdgcn_exp2f(-dl);
; #pragma unroll
;     for (int r = 0; r < 16; ++r) { p0[r] -= dl; p1[r] -= dl; }
;     const float nm = -mref;
; #pragma unroll
;     for (int r = 0; r < 16; ++r) negm[r] = nm; }
; #pragma unroll
;   for (int r = 0; r < 16; ++r) p0[r] = __builtin_amdgcn_exp2f(p0[r]);
; }
; __device__ __forceinline__ void attn_unit(const bf16_t* __restrict__ Qb, const bf16_t* __restrict__ KNh, const bf16_t* __restrict__ KRb, const bf16_t* __restrict__ Vh, bf16_t* __restrict__ Ob, char* lds) {
;     ...
;   SLOAD(0, 0); SLOAD(1, KVBLK); asm volatile("s_waitcnt vmcnt(0)" ::: "memory"); SWRITE(0, 0); SWRITE(1, 1); SLOAD(0, 2 * KVBLK); ABAR();
;   qkt(pA0, pA1, K_lds, qr, negm, r32, hi); partialSM<true>(pA0, pA1, mref, negm, alA);
;   SWRITE(2, 0); SLOAD(1, 3 * KVBLK); ABAR();
	v_mfma_f32_32x32x16_bf16 v[16:31], v[50:53], v[112:115], v[16:31]
	v_max_f32_e32 v48, v49, v48
	v_max3_f32 v48, v48, v34, v35
	v_max3_f32 v48, v48, v36, v37
	v_max3_f32 v48, v48, v38, v39
	v_max3_f32 v48, v48, v40, v41
	v_max3_f32 v48, v48, v42, v43
	v_max3_f32 v48, v48, v44, v45
	v_max3_f32 v48, v48, v46, v47
	s_nop 3
	v_max3_f32 v48, v48, v16, v17
	v_max3_f32 v48, v48, v18, v19
	v_max3_f32 v48, v48, v20, v21
	v_max3_f32 v48, v48, v22, v23
	v_max3_f32 v48, v48, v24, v25
	v_max3_f32 v48, v48, v26, v27
	v_max3_f32 v48, v48, v28, v29
	v_max3_f32 v48, v48, v30, v31
	v_mov_b32_e32 v49, v48
	s_nop 1
	v_permlane32_swap_b32_e32 v48, v49
	v_max_f32_e32 v49, v49, v49
	v_max_f32_e32 v48, v48, v48
	v_max_f32_e32 v48, v48, v49
	v_sub_f32_e32 v64, v16, v48
	v_add_u32_e32 v16, s83, v201
	v_sub_f32_e32 v49, v32, v48
	v_sub_f32_e32 v33, v33, v48
	v_sub_f32_e32 v34, v34, v48
	v_sub_f32_e32 v35, v35, v48
	v_sub_f32_e32 v36, v36, v48
	v_sub_f32_e32 v37, v37, v48
	v_sub_f32_e32 v38, v38, v48
	v_sub_f32_e32 v39, v39, v48
	v_sub_f32_e32 v40, v40, v48
	v_sub_f32_e32 v41, v41, v48
	v_sub_f32_e32 v42, v42, v48
	v_sub_f32_e32 v43, v43, v48
	v_sub_f32_e32 v44, v44, v48
	v_sub_f32_e32 v45, v45, v48
	v_sub_f32_e32 v46, v46, v48
	v_sub_f32_e32 v47, v47, v48
	s_waitcnt vmcnt(4)
	ds_write_b128 v16, v[140:143]
	v_add_u32_e32 v16, s83, v202
	s_add_i32 s46, s85, 0x4000
	v_add_u32_e32 v243, s46, v206
	ds_read_b128 v[244:247], v243
	ds_read_b128 v[248:251], v243 offset:8192
	v_exp_f32_e32 v194, v49
	v_exp_f32_e32 v216, v33
	v_exp_f32_e32 v192, v34
	v_exp_f32_e32 v195, v35
	v_exp_f32_e32 v190, v36
	v_exp_f32_e32 v193, v37
	v_exp_f32_e32 v189, v38
	v_exp_f32_e32 v191, v39
	v_exp_f32_e32 v186, v40
	v_exp_f32_e32 v188, v41
	v_exp_f32_e32 v185, v42
	v_exp_f32_e32 v187, v43
	v_exp_f32_e32 v181, v44
	v_exp_f32_e32 v183, v45
	v_exp_f32_e32 v180, v46
	v_exp_f32_e32 v182, v47
	s_waitcnt vmcnt(3)
	ds_write_b64 v16, v[172:173]
	v_add_f32_e32 v161, 0, v48
	s_waitcnt lgkmcnt(0)
	s_barrier
	v_sub_f32_e32 v79, v31, v48
	v_sub_f32_e32 v78, v30, v48
	v_sub_f32_e32 v77, v29, v48
	v_sub_f32_e32 v76, v28, v48
	v_sub_f32_e32 v75, v27, v48
	v_sub_f32_e32 v74, v26, v48
	v_sub_f32_e32 v73, v25, v48
	v_sub_f32_e32 v72, v24, v48
	v_sub_f32_e32 v71, v23, v48
	v_sub_f32_e32 v70, v22, v48
	v_sub_f32_e32 v69, v21, v48
	v_sub_f32_e32 v68, v20, v48
	v_sub_f32_e32 v67, v19, v48
	v_sub_f32_e32 v66, v18, v48
	v_sub_f32_e32 v65, v17, v48
	v_xor_b32_e32 v32, 0x80000000, v161
	v_mov_b64_e32 v[30:31], v[14:15]
	v_mov_b64_e32 v[28:29], v[12:13]
	v_mov_b64_e32 v[26:27], v[10:11]
	v_mov_b64_e32 v[24:25], v[8:9]
	v_mov_b64_e32 v[22:23], v[6:7]
	v_mov_b64_e32 v[20:21], v[4:5]
	v_mov_b64_e32 v[18:19], v[2:3]
	v_mov_b64_e32 v[16:17], v[0:1]
	v_mov_b32_e32 v33, v32
	v_mov_b32_e32 v34, v32
	v_mov_b32_e32 v35, v32
	v_mov_b32_e32 v36, v32
	v_mov_b32_e32 v37, v32
	v_mov_b32_e32 v38, v32
	v_mov_b32_e32 v39, v32
	v_mov_b32_e32 v40, v32
	v_mov_b32_e32 v41, v32
	v_mov_b32_e32 v42, v32
	v_mov_b32_e32 v43, v32
	v_mov_b32_e32 v44, v32
	v_mov_b32_e32 v45, v32
	v_mov_b32_e32 v46, v32
	v_mov_b32_e32 v47, v32
; #define SBAR() __builtin_amdgcn_sched_barrier(0)
; #define ABAR() asm volatile("s_waitcnt lgkmcnt(0)\n\ts_barrier" ::: "memory")
; #define SLOAD(i, k0) do { const bf16_t* vt_ = Vh + (size_t)(k0) * 512; const bf16_t* kt_ = KNh + (size_t)(k0) * 512; const bf16_t* rt_ = KRb + (size_t)(k0) * 32; \
;     sr_[i].vs = *reinterpret_cast<const bf16x8*>(vt_ + lo_kv); sr_[i].ks = *reinterpret_cast<const bf16x8*>(kt_ + lo_kv); sr_[i].kr = *reinterpret_cast<const s16x4*>(rt_ + lo_kr); } while (0)
; #define SWRITE(slot, i) do { *(bf16x8*)(V_lds + (slot) * SHM_V + vst) = sr_[i].vs; *(bf16x8*)(K_lds + (slot) * SHM_K + kst) = sr_[i].ks; *(s16x4*)(K_lds + (slot) * SHM_K + krst) = sr_[i].kr; } while (0)
; #define RESC(a) do { if (__any((a) < 1.f)) { if (hi == 0) al_l[r32] = (a); asm volatile("s_waitcnt lgkmcnt(0)" ::: "memory"); \
;     _Pragma("unroll") for (int d = 0; d < 2; ++d) _Pragma("unroll") for (int r = 0; r < 16; ++r) o[d][r] *= al_l[crow(r, hi)]; } } while (0)
; __device__ __forceinline__ void attn_unit(const bf16_t* __restrict__ Qb, const bf16_t* __restrict__ KNh, const bf16_t* __restrict__ KRb, const bf16_t* __restrict__ Vh, bf16_t* __restrict__ Ob, char* lds) {
;     ...
;   for (int j = 1; j + 1 < NT; j += 2) {
;     SBAR(); qkt(pB0, pB1, K_lds + (j & 3) * SHM_K, qr, negm, r32, hi);
;     finishSM(pA0, pA1, alA, l_reg, pa0, pa1, pa2, pa3); SBAR();
;     if (j + 2 < NT) { SWRITE((j + 2) & 3, 1); } if (j + 3 < NT) { SLOAD(0, (j + 3) * KVBLK); } SBAR();
;     pv_d0(o, vb0 + ((j - 1) & 3) * SHM_V, pa0, pa1, pa2, pa3); partialSM<false>(pB0, pB1, mref, negm, alB);
;     RESC(alB); ABAR();
.LBB0_739:
	s_add_i32 s41, s89, 0xffff4000
	s_and_b32 s41, s41, 0xc000
	s_add_i32 s42, s85, s41
	v_add_u32_e32 v56, s42, v207
	v_mfma_f32_32x32x16_bf16 v[96:111], v[244:247], v[132:135], v[32:47]
	ds_read_b128 v[48:51], v56
	ds_read_b128 v[56:59], v56 offset:8192
	v_add_u32_e32 v60, s42, v208
	v_add_u32_e32 v165, s42, v209
	v_add_u32_e32 v167, s42, v210
	v_exp_f32_e32 v64, v64
	v_exp_f32_e32 v65, v65
	v_exp_f32_e32 v66, v66
	v_exp_f32_e32 v67, v67
	v_exp_f32_e32 v68, v68
	v_mfma_f32_32x32x16_bf16 v[80:95], v[248:251], v[132:135], v[32:47]
	ds_read_b128 v[52:55], v60
	ds_read_b128 v[60:63], v60 offset:8192
	ds_read_b128 v[220:223], v165
	ds_read_b128 v[224:227], v165 offset:8192
	ds_read_b128 v[228:231], v167
	ds_read_b128 v[232:235], v167 offset:8192
	v_exp_f32_e32 v69, v69
	v_exp_f32_e32 v70, v70
	v_exp_f32_e32 v71, v71
	v_add_u32_e32 v169, s42, v211
	v_exp_f32_e32 v72, v72
	v_exp_f32_e32 v73, v73
	s_waitcnt lgkmcnt(7)
	v_mfma_f32_32x32x16_bf16 v[96:111], v[48:51], v[128:131], v[96:111]
	ds_read_b128 v[48:51], v169
	ds_read_b128 v[236:239], v169 offset:8192
	v_exp_f32_e32 v74, v74
	v_exp_f32_e32 v75, v75
	v_exp_f32_e32 v76, v76
	v_exp_f32_e32 v77, v77
	v_exp_f32_e32 v78, v78
	v_exp_f32_e32 v79, v79
	s_waitcnt lgkmcnt(8)
	v_mfma_f32_32x32x16_bf16 v[80:95], v[56:59], v[128:131], v[80:95]
	s_waitcnt lgkmcnt(7)
	v_mfma_f32_32x32x16_bf16 v[96:111], v[52:55], v[124:127], v[96:111]
	v_add_f32_e32 v52, 0, v194
	v_add_f32_e32 v52, v216, v52
	v_add_f32_e32 v52, v192, v52
	v_add_f32_e32 v52, v195, v52
	v_add_f32_e32 v52, v190, v52
	v_add_f32_e32 v52, v193, v52
	v_add_f32_e32 v52, v189, v52
	s_waitcnt lgkmcnt(6)
	v_mfma_f32_32x32x16_bf16 v[80:95], v[60:63], v[124:127], v[80:95]
	v_add_f32_e32 v52, v191, v52
	v_add_f32_e32 v52, v186, v52
	v_add_f32_e32 v52, v188, v52
	v_add_f32_e32 v52, v185, v52
	v_add_f32_e32 v52, v187, v52
	v_add_f32_e32 v52, v181, v52
	v_add_f32_e32 v52, v183, v52
	s_waitcnt lgkmcnt(5)
	v_mfma_f32_32x32x16_bf16 v[96:111], v[220:223], v[120:123], v[96:111]
	v_add_f32_e32 v52, v180, v52
	v_add_f32_e32 v52, v182, v52
	v_add_f32_e32 v52, v64, v52
	v_add_f32_e32 v52, v65, v52
	v_add_f32_e32 v52, v66, v52
	v_add_f32_e32 v52, v67, v52
	v_add_f32_e32 v52, v68, v52
	s_waitcnt lgkmcnt(4)
	v_mfma_f32_32x32x16_bf16 v[80:95], v[224:227], v[120:123], v[80:95]
	v_add_f32_e32 v52, v69, v52
	v_add_f32_e32 v52, v70, v52
	v_add_f32_e32 v52, v71, v52
	v_add_f32_e32 v52, v72, v52
	v_add_f32_e32 v52, v73, v52
	v_add_f32_e32 v52, v74, v52
	v_add_f32_e32 v52, v75, v52
	s_waitcnt lgkmcnt(3)
	v_mfma_f32_32x32x16_bf16 v[96:111], v[228:231], v[116:119], v[96:111]
	v_add_f32_e32 v52, v76, v52
	v_add_f32_e32 v52, v77, v52
	v_add_f32_e32 v52, v78, v52
	v_add_f32_e32 v165, v79, v52
	v_mov_b32_e32 v167, v165
	s_nop 1
	v_permlane32_swap_b32_e32 v165, v167
	s_waitcnt lgkmcnt(2)
	v_mfma_f32_32x32x16_bf16 v[80:95], v[232:235], v[116:119], v[80:95]
	v_cvt_pk_bf16_f32 v60, v194, v216
	v_cvt_pk_bf16_f32 v61, v192, v195
	v_cvt_pk_bf16_f32 v62, v190, v193
	v_cvt_pk_bf16_f32 v63, v189, v191
	v_cvt_pk_bf16_f32 v56, v186, v188
	v_cvt_pk_bf16_f32 v57, v185, v187
	v_cvt_pk_bf16_f32 v58, v181, v183
	s_waitcnt lgkmcnt(1)
	v_mfma_f32_32x32x16_bf16 v[96:111], v[48:51], v[112:115], v[96:111]
	v_cvt_pk_bf16_f32 v59, v180, v182
	v_cvt_pk_bf16_f32 v52, v64, v65
	v_cvt_pk_bf16_f32 v53, v66, v67
	v_cvt_pk_bf16_f32 v54, v68, v69
	v_cvt_pk_bf16_f32 v55, v70, v71
	v_cvt_pk_bf16_f32 v48, v72, v73
	v_cvt_pk_bf16_f32 v49, v74, v75
	s_waitcnt lgkmcnt(0)
	v_mfma_f32_32x32x16_bf16 v[80:95], v[236:239], v[112:115], v[80:95]
	v_cvt_pk_bf16_f32 v50, v76, v77
	v_cvt_pk_bf16_f32 v51, v78, v79
	s_add_i32 s42, s89, 0xffffc000
	s_and_b32 s42, s42, 0xc000
	s_add_i32 s43, s85, s42
	s_cmp_lt_u32 s90, 29
	s_cselect_b64 s[44:45], -1, 0
	s_cmp_gt_u32 s90, 28
	v_add_u32_e32 v64, s43, v202
	v_add_u32_e32 v65, s43, v201
	v_add_u32_e32 v66, s42, v204
	s_cselect_b64 s[42:43], -1, 0
	s_and_b64 vcc, exec, s[42:43]
	s_waitcnt vmcnt(2)
	ds_write_b128 v66, v[144:147]
	s_waitcnt vmcnt(1)
	ds_write_b128 v65, v[148:151]
	s_waitcnt vmcnt(0)
	ds_write_b64 v64, v[174:175]
	s_cbranch_vccnz .LBB0_741
	global_load_dwordx4 v[136:139], v240, s[98:99]
	global_load_dwordx4 v[140:143], v241, s[98:99]
	global_load_dwordx2 v[172:173], v242, s[100:101]
	s_add_u32 s98, s98, 0x10000
	s_addc_u32 s99, s99, 0
	s_add_u32 s100, s100, 0x1000
	s_addc_u32 s101, s101, 0
.LBB0_741:
	s_and_b32 s48, s89, 0xc000
	v_add_u32_e32 v169, s48, v203
	ds_read_b64_tr_b16 v[64:65], v169
	ds_read_b64_tr_b16 v[66:67], v169 offset:2048
	ds_read_b64_tr_b16 v[70:71], v169 offset:2560
	ds_read_b64_tr_b16 v[68:69], v169 offset:512
	s_waitcnt lgkmcnt(2)
	v_mfma_f32_32x32x16_bf16 v[0:15], v[60:63], v[64:67], v[0:15]
	ds_read_b64_tr_b16 v[64:65], v169 offset:4096
	ds_read_b64_tr_b16 v[66:67], v169 offset:6144
	ds_read_b64_tr_b16 v[74:75], v169 offset:6656
	ds_read_b64_tr_b16 v[72:73], v169 offset:4608
	s_waitcnt lgkmcnt(2)
	v_mfma_f32_32x32x16_bf16 v[0:15], v[56:59], v[64:67], v[0:15]
	ds_read_b64_tr_b16 v[64:65], v169 offset:8192
	ds_read_b64_tr_b16 v[66:67], v169 offset:10240
	ds_read_b64_tr_b16 v[78:79], v169 offset:10752
	ds_read_b64_tr_b16 v[76:77], v169 offset:8704
	v_mfma_f32_32x32x16_bf16 v[16:31], v[60:63], v[68:71], v[16:31]
	s_waitcnt lgkmcnt(2)
	v_mfma_f32_32x32x16_bf16 v[0:15], v[52:55], v[64:67], v[0:15]
	ds_read_b64_tr_b16 v[64:65], v169 offset:12288
	ds_read_b64_tr_b16 v[66:67], v169 offset:14336
	ds_read_b64_tr_b16 v[186:187], v169 offset:14848
	ds_read_b64_tr_b16 v[184:185], v169 offset:12800
	v_mfma_f32_32x32x16_bf16 v[16:31], v[56:59], v[72:75], v[16:31]
	s_waitcnt lgkmcnt(2)
	v_mfma_f32_32x32x16_bf16 v[0:15], v[48:51], v[64:67], v[0:15]
	v_max_f32_e32 v64, v97, v97
	v_max_f32_e32 v65, v96, v96
	v_max_f32_e32 v64, v65, v64
	v_max3_f32 v64, v64, v98, v99
	v_max3_f32 v60, v64, v100, v101
	v_max3_f32 v60, v60, v102, v103
	v_max3_f32 v60, v60, v104, v105
	v_max3_f32 v60, v60, v106, v107
	v_max3_f32 v60, v60, v108, v109
	v_mfma_f32_32x32x16_bf16 v[16:31], v[52:55], v[76:79], v[16:31]
	v_max3_f32 v60, v60, v110, v111
	v_max3_f32 v60, v60, v80, v81
	v_max3_f32 v56, v60, v82, v83
	v_max3_f32 v56, v56, v84, v85
	v_max3_f32 v56, v56, v86, v87
	v_max3_f32 v56, v56, v88, v89
	v_max3_f32 v56, v56, v90, v91
	v_max3_f32 v56, v56, v92, v93
	s_waitcnt lgkmcnt(0)
	v_mfma_f32_32x32x16_bf16 v[16:31], v[48:51], v[184:187], v[16:31]
	s_add_i32 s46, s89, 0xffff8000
	s_and_b32 s46, s46, 0xc000
	s_add_i32 s46, s46, 0x10000
	v_add_u32_e32 v243, s46, v206
	ds_read_b128 v[244:247], v243
	ds_read_b128 v[248:251], v243 offset:8192
	v_max3_f32 v56, v56, v94, v95
	v_mov_b32_e32 v52, v56
	s_nop 1
	v_permlane32_swap_b32_e32 v56, v52
	v_max_f32_e32 v52, v52, v52
	v_max_f32_e32 v53, v56, v56
	v_max_f32_e32 v52, v53, v52
	v_cmp_ge_f32_e32 vcc, s86, v52
	s_cmp_eq_u64 vcc, exec
	s_cbranch_scc0 .LBB0_757
	v_mov_b32_e32 v169, 1.0
	v_cmp_gt_f32_e32 vcc, 1.0, v169
	s_cbranch_vccz .LBB0_746

; #define PK4(P, BASE, OUT) do { u32x4 w = {cvt_pk_bf16(P[BASE + 0], P[BASE + 1]), cvt_pk_bf16(P[BASE + 2], P[BASE + 3]), cvt_pk_bf16(P[BASE + 4], P[BASE + 5]), cvt_pk_bf16(P[BASE + 6], P[BASE + 7])}; \
;     OUT = *reinterpret_cast<bf16x8*>(&w); } while (0)
; __device__ __forceinline__ void finishSM(f32x16& p0, f32x16& p1, float alpha, float& l_reg, bf16x8& pa0, bf16x8& pa1, bf16x8& pa2, bf16x8& pa3) {
; #pragma unroll
;   for (int r = 0; r < 16; ++r) p1[r] = __builtin_amdgcn_exp2f(p1[r]);
;   float ps = 0;
; #pragma unroll
;   for (int r = 0; r < 16; ++r) ps += p0[r];
; #pragma unroll
;   for (int r = 0; r < 16; ++r) ps += p1[r];
;   { auto rr = __builtin_amdgcn_permlane32_swap(__float_as_uint(ps), __float_as_uint(ps), false, false);
;     ps = __uint_as_float(rr[0]) + __uint_as_float(rr[1]); }
;   l_reg = l_reg * alpha + ps;
;     ...
;   PK4(p0, 0, pa0); PK4(p0, 8, pa1); PK4(p1, 0, pa2); PK4(p1, 8, pa3);
;     ...
; }
; __device__ __forceinline__ void qkt(f32x16& p0, f32x16& p1, const char* Ks, const bf16x8* qr, const f32x16& negm, int r32, int hi) {
;   p0 = negm; p1 = negm;
; #pragma unroll
;   for (int d0 = 0; d0 < 6; ++d0) { int cb = (d0 * 16 + hi * 8) * 2;
;     bf16x8 b0 = *reinterpret_cast<const bf16x8*>(Ks + KSWZ(r32, cb));
;     bf16x8 b1 = *reinterpret_cast<const bf16x8*>(Ks + KSWZ(32 + r32, cb));
;     p0 = __builtin_amdgcn_mfma_f32_32x32x16_bf16(b0, qr[d0], p0, 0, 0, 0);
;     p1 = __builtin_amdgcn_mfma_f32_32x32x16_bf16(b1, qr[d0], p1, 0, 0, 0); }
; }
.LBB0_746:
	s_waitcnt lgkmcnt(0)
	s_barrier
	v_exp_f32_e32 v192, v96
	v_exp_f32_e32 v193, v97
	v_exp_f32_e32 v194, v98
	v_exp_f32_e32 v195, v99
	v_exp_f32_e32 v216, v100
	v_exp_f32_e32 v217, v101
	v_exp_f32_e32 v219, v102
	v_exp_f32_e32 v220, v103
	v_exp_f32_e32 v221, v104
	v_exp_f32_e32 v222, v105
	v_exp_f32_e32 v223, v106
	v_exp_f32_e32 v224, v107
	v_exp_f32_e32 v225, v108
	v_exp_f32_e32 v226, v109
	v_exp_f32_e32 v227, v110
	v_exp_f32_e32 v228, v111
	s_add_i32 s46, s89, 0xffff8000
	s_and_b32 s46, s46, 0xc000
	s_add_i32 s46, s46, 0x10000
	v_add_u32_e32 v171, s46, v207
	v_mfma_f32_32x32x16_bf16 v[96:111], v[244:247], v[132:135], v[32:47]
	ds_read_b128 v[184:187], v171
	ds_read_b128 v[188:191], v171 offset:8192
	v_add_u32_e32 v171, s46, v208
	v_exp_f32_e32 v80, v80
	v_exp_f32_e32 v81, v81
	v_exp_f32_e32 v82, v82
	v_exp_f32_e32 v83, v83
	v_exp_f32_e32 v87, v87
	v_mfma_f32_32x32x16_bf16 v[64:79], v[248:251], v[132:135], v[32:47]
	ds_read_b128 v[244:247], v171
	ds_read_b128 v[248:251], v171 offset:8192
	v_add_u32_e32 v171, s46, v209
	v_exp_f32_e32 v229, v92
	v_exp_f32_e32 v230, v93
	v_exp_f32_e32 v231, v94
	v_exp_f32_e32 v232, v95
	s_waitcnt lgkmcnt(3)
	v_mfma_f32_32x32x16_bf16 v[96:111], v[184:187], v[128:131], v[96:111]
	s_waitcnt lgkmcnt(2)
	v_mfma_f32_32x32x16_bf16 v[64:79], v[188:191], v[128:131], v[64:79]
	ds_read_b128 v[184:187], v171
	ds_read_b128 v[188:191], v171 offset:8192
	v_add_u32_e32 v171, s46, v210
	s_waitcnt lgkmcnt(3)
	v_mfma_f32_32x32x16_bf16 v[96:111], v[244:247], v[124:127], v[96:111]
	s_waitcnt lgkmcnt(2)
	v_mfma_f32_32x32x16_bf16 v[64:79], v[248:251], v[124:127], v[64:79]
	ds_read_b128 v[244:247], v171
	ds_read_b128 v[248:251], v171 offset:8192
	v_add_u32_e32 v171, s46, v211
	s_waitcnt lgkmcnt(3)
	v_mfma_f32_32x32x16_bf16 v[96:111], v[184:187], v[120:123], v[96:111]
	s_waitcnt lgkmcnt(2)
	v_mfma_f32_32x32x16_bf16 v[64:79], v[188:191], v[120:123], v[64:79]
	ds_read_b128 v[184:187], v171
	ds_read_b128 v[188:191], v171 offset:8192
	s_waitcnt lgkmcnt(3)
	v_mfma_f32_32x32x16_bf16 v[96:111], v[244:247], v[116:119], v[96:111]
	s_waitcnt lgkmcnt(2)
	v_mfma_f32_32x32x16_bf16 v[64:79], v[248:251], v[116:119], v[64:79]
	v_cvt_pk_bf16_f32 v92, v192, v193
	v_cvt_pk_bf16_f32 v93, v194, v195
	v_cvt_pk_bf16_f32 v94, v216, v217
	v_cvt_pk_bf16_f32 v95, v219, v220
	s_waitcnt lgkmcnt(1)
	v_mfma_f32_32x32x16_bf16 v[96:111], v[184:187], v[112:115], v[96:111]
	v_exp_f32_e32 v185, v84
	v_add_f32_e32 v84, 0, v192
	v_add_f32_e32 v84, v193, v84
	v_add_f32_e32 v84, v194, v84
	v_add_f32_e32 v84, v195, v84
	v_add_f32_e32 v84, v216, v84
	v_add_f32_e32 v84, v217, v84
	v_add_f32_e32 v84, v219, v84
	v_add_f32_e32 v84, v220, v84
	v_add_f32_e32 v84, v221, v84
	v_add_f32_e32 v84, v222, v84
	v_add_f32_e32 v84, v223, v84
	v_add_f32_e32 v84, v224, v84
	v_add_f32_e32 v84, v225, v84
	v_add_f32_e32 v84, v226, v84
	v_add_f32_e32 v84, v227, v84
	v_add_f32_e32 v84, v228, v84
	v_add_f32_e32 v84, v80, v84
	v_exp_f32_e32 v186, v85
	v_add_f32_e32 v84, v81, v84
	v_exp_f32_e32 v187, v86
	v_add_f32_e32 v84, v82, v84
	v_add_f32_e32 v84, v83, v84
	s_waitcnt lgkmcnt(0)
	v_mfma_f32_32x32x16_bf16 v[64:79], v[188:191], v[112:115], v[64:79]
	v_exp_f32_e32 v188, v88
	v_add_f32_e32 v84, v185, v84
	v_exp_f32_e32 v189, v89
	v_add_f32_e32 v84, v186, v84
	v_exp_f32_e32 v190, v90
	v_add_f32_e32 v84, v187, v84
	v_exp_f32_e32 v191, v91
	v_add_f32_e32 v84, v87, v84
	v_add_f32_e32 v84, v188, v84
	v_add_f32_e32 v84, v189, v84
	v_add_f32_e32 v84, v190, v84
	v_add_f32_e32 v84, v191, v84
	v_add_f32_e32 v84, v229, v84
	v_add_f32_e32 v84, v230, v84
	v_add_f32_e32 v84, v231, v84
	v_add_f32_e32 v171, v232, v84
	v_mov_b32_e32 v184, v171
	s_nop 1
	v_permlane32_swap_b32_e32 v171, v184
	v_cvt_pk_bf16_f32 v88, v221, v222
	v_cvt_pk_bf16_f32 v89, v223, v224
	v_cvt_pk_bf16_f32 v90, v225, v226
	v_cvt_pk_bf16_f32 v91, v227, v228
	v_cvt_pk_bf16_f32 v84, v80, v81
	v_cvt_pk_bf16_f32 v85, v82, v83
	v_cvt_pk_bf16_f32 v86, v185, v186
	v_cvt_pk_bf16_f32 v87, v187, v87
	v_cvt_pk_bf16_f32 v80, v188, v189
	v_cvt_pk_bf16_f32 v81, v190, v191
	v_cvt_pk_bf16_f32 v82, v229, v230
	v_cvt_pk_bf16_f32 v83, v231, v232
	s_andn2_b64 vcc, exec, s[44:45]
	s_cbranch_vccnz .LBB0_748
	s_add_i32 s44, s48, 0
	v_add_u32_e32 v185, s48, v204
	s_add_i32 s44, s44, 0x10000
	v_add_u32_e32 v186, s44, v201
	v_add_u32_e32 v187, s44, v202
	s_waitcnt vmcnt(2)
	ds_write_b128 v185, v[136:139]
	s_waitcnt vmcnt(1)
	ds_write_b128 v186, v[140:143]
	s_waitcnt vmcnt(0)
	ds_write_b64 v187, v[172:173]

; __device__ __forceinline__ s16x4 vtr(lds_cptr p) { return __builtin_bit_cast(s16x4, __builtin_amdgcn_ds_read_tr16_b64_v4i16((LAS v4i16_t*)p)); }
; template <bool FIRST> __device__ __forceinline__ void partialSM(f32x16& p0, f32x16& p1, float& mref, f32x16& negm, float& alpha) {
;   constexpr float THRL = THR * 1.4426950408889634f;
;   float pmax = p0[0];
; #pragma unroll
;   for (int r = 1; r < 16; ++r) pmax = fmaxf(pmax, p0[r]);
; #pragma unroll
;   for (int r = 0; r < 16; ++r) pmax = fmaxf(pmax, p1[r]);
;   { auto rr = __builtin_amdgcn_permlane32_swap(__float_as_uint(pmax), __float_as_uint(pmax), false, false);
;     pmax = fmaxf(__uint_as_float(rr[0]), __uint_as_float(rr[1])); }
;   if (!FIRST && __builtin_expect(__all(pmax <= THRL), 1)) { alpha = 1.f; }
; template <int D0> __device__ __forceinline__ void pv_one(f32x16& od, lds_cptr vp, bf16x8 pa0, bf16x8 pa1, bf16x8 pa2, bf16x8 pa3) {
;   const s16x4 l0 = vtr(vp + v_rd_off(D0, 0, 0)), h0 = vtr(vp + v_rd_off(D0, 0, 1)), l1 = vtr(vp + v_rd_off(D0, 1, 0)), h1 = vtr(vp + v_rd_off(D0, 1, 1));
;   const s16x4 l2 = vtr(vp + v_rd_off(D0, 2, 0)), h2 = vtr(vp + v_rd_off(D0, 2, 1)), l3 = vtr(vp + v_rd_off(D0, 3, 0)), h3 = vtr(vp + v_rd_off(D0, 3, 1));
;     ...
;   od = __builtin_amdgcn_mfma_f32_32x32x16_bf16(pa0, PK(l0, h0), od, 0, 0, 0);
;   od = __builtin_amdgcn_mfma_f32_32x32x16_bf16(pa1, PK(l1, h1), od, 0, 0, 0);
;   od = __builtin_amdgcn_mfma_f32_32x32x16_bf16(pa2, PK(l2, h2), od, 0, 0, 0);
;   od = __builtin_amdgcn_mfma_f32_32x32x16_bf16(pa3, PK(l3, h3), od, 0, 0, 0);
;     ...
; }
; __device__ __forceinline__ void pv_d0(f32x16* o, lds_cptr vp, bf16x8 pa0, bf16x8 pa1, bf16x8 pa2, bf16x8 pa3) {
;   pv_one<0>(o[0], vp, pa0, pa1, pa2, pa3); pv_one<1>(o[1], vp, pa0, pa1, pa2, pa3);
; }
.LBB0_750:
	v_add_u32_e32 v185, s41, v203
	ds_read_b64_tr_b16 v[180:181], v185
	ds_read_b64_tr_b16 v[182:183], v185 offset:2048
	ds_read_b64_tr_b16 v[188:189], v185 offset:2560
	ds_read_b64_tr_b16 v[186:187], v185 offset:512
	s_waitcnt lgkmcnt(2)
	v_mfma_f32_32x32x16_bf16 v[0:15], v[92:95], v[180:183], v[0:15]
	ds_read_b64_tr_b16 v[180:181], v185 offset:4096
	ds_read_b64_tr_b16 v[182:183], v185 offset:6144
	ds_read_b64_tr_b16 v[192:193], v185 offset:6656
	ds_read_b64_tr_b16 v[190:191], v185 offset:4608
	s_waitcnt lgkmcnt(2)
	v_mfma_f32_32x32x16_bf16 v[0:15], v[88:91], v[180:183], v[0:15]
	ds_read_b64_tr_b16 v[180:181], v185 offset:8192
	ds_read_b64_tr_b16 v[182:183], v185 offset:10240
	ds_read_b64_tr_b16 v[222:223], v185 offset:10752
	ds_read_b64_tr_b16 v[220:221], v185 offset:8704
	v_mfma_f32_32x32x16_bf16 v[16:31], v[92:95], v[186:189], v[16:31]
	s_waitcnt lgkmcnt(2)
	v_mfma_f32_32x32x16_bf16 v[0:15], v[84:87], v[180:183], v[0:15]
	ds_read_b64_tr_b16 v[180:181], v185 offset:12288
	ds_read_b64_tr_b16 v[182:183], v185 offset:14336
	ds_read_b64_tr_b16 v[226:227], v185 offset:14848
	ds_read_b64_tr_b16 v[224:225], v185 offset:12800
	v_mfma_f32_32x32x16_bf16 v[16:31], v[88:91], v[190:193], v[16:31]
	s_waitcnt lgkmcnt(2)
	v_mfma_f32_32x32x16_bf16 v[0:15], v[80:83], v[180:183], v[0:15]
	v_max_f32_e32 v180, v97, v97
	v_max_f32_e32 v181, v96, v96
	v_max_f32_e32 v180, v181, v180
	v_max3_f32 v180, v180, v98, v99
	v_max3_f32 v180, v180, v100, v101
	v_max3_f32 v92, v180, v102, v103
	v_max3_f32 v92, v92, v104, v105
	v_max3_f32 v92, v92, v106, v107
	v_max3_f32 v92, v92, v108, v109
	v_mfma_f32_32x32x16_bf16 v[16:31], v[84:87], v[220:223], v[16:31]
	v_max3_f32 v92, v92, v110, v111
	v_max3_f32 v92, v92, v64, v65
	v_max3_f32 v92, v92, v66, v67
	v_max3_f32 v88, v92, v68, v69
	v_max3_f32 v88, v88, v70, v71
	v_max3_f32 v88, v88, v72, v73
	v_max3_f32 v88, v88, v74, v75
	v_max3_f32 v88, v88, v76, v77
	s_waitcnt lgkmcnt(0)
	v_mfma_f32_32x32x16_bf16 v[16:31], v[80:83], v[224:227], v[16:31]
	s_add_i32 s46, s89, 0xffffc000
	s_and_b32 s46, s46, 0xc000
	s_add_i32 s46, s85, s46
	v_add_u32_e32 v243, s46, v206
	ds_read_b128 v[244:247], v243
	ds_read_b128 v[248:251], v243 offset:8192
	v_max3_f32 v88, v88, v78, v79
	v_mov_b32_e32 v89, v88
	s_nop 1
	v_permlane32_swap_b32_e32 v88, v89
	v_max_f32_e32 v84, v89, v89
	v_max_f32_e32 v85, v88, v88
	v_max_f32_e32 v85, v85, v84
	v_cmp_ge_f32_e32 vcc, s86, v85
	s_cmp_eq_u64 vcc, exec
	v_mov_b32_e32 v84, 1.0
	s_cbranch_scc0 .LBB0_758
	v_cmp_gt_f32_e32 vcc, 1.0, v84
	s_cbranch_vccz .LBB0_755
